# down-GEMM residual epilogue rewritten by hand: residual loads issued 8 at a time one round ahead, DPP row reductions instead of ds_bpermute
# speedup vs baseline: 1.0064x; 1.0064x over previous
; #define MFMA(a, b, c) __builtin_amdgcn_mfma_f32_32x32x16_bf16((a), (b), (c), 0, 0, 0)
; #define DSR(dst, addr, off) asm volatile("ds_read_b128 %0, %1 offset:" #off : "=&v"(dst) : "v"(addr))
; template <bool VT>
; DI void g_compute_asm(unsigned aA0, unsigned aA1, unsigned aB0, unsigned aB1, f32x16 (&acc)[4][2]) {
;   bf16x8 a0[4], a1[4], b0[2], b1[2];
;   DSR(b0[0], aB0, 0); DSR(b0[1], aB0, 2048);
;   DSR(a0[0], aA0, 0); DSR(a0[1], aA0, 2048); DSR(a0[2], aA0, 4096); DSR(a0[3], aA0, 6144);
;   DSR(b1[0], aB1, 0); DSR(b1[1], aB1, 2048);
;   DSR(a1[0], aA1, 0); DSR(a1[1], aA1, 2048); DSR(a1[2], aA1, 4096); DSR(a1[3], aA1, 6144);
;   asm volatile("s_waitcnt lgkmcnt(6)" : "+v"(b0[0]), "+v"(b0[1]), "+v"(a0[0]), "+v"(a0[1]), "+v"(a0[2]), "+v"(a0[3]));
; #pragma unroll
;   for (int mi = 0; mi < 4; ++mi)
; #pragma unroll
;     for (int ni = 0; ni < 2; ++ni) {
;       if (VT) acc[mi][ni] = MFMA(a0[mi], b0[ni], acc[mi][ni]);
;       else acc[mi][ni] = MFMA(b0[ni], a0[mi], acc[mi][ni]);
;     }
;   __builtin_amdgcn_sched_barrier(0);
;   asm volatile("s_waitcnt lgkmcnt(0)" : "+v"(b1[0]), "+v"(b1[1]), "+v"(a1[0]), "+v"(a1[1]), "+v"(a1[2]), "+v"(a1[3]));
; #pragma unroll
;   for (int mi = 0; mi < 4; ++mi)
; #pragma unroll
;     for (int ni = 0; ni < 2; ++ni) {
;       if (VT) acc[mi][ni] = MFMA(a1[mi], b1[ni], acc[mi][ni]);
;       else acc[mi][ni] = MFMA(b1[ni], a1[mi], acc[mi][ni]);
;     }
; }
; template <bool VT>
; DI int gemm_kloop(const bf16_t* Ag, size_t lda, const bf16_t* Bg, size_t ldb, int nk, bf16_t* ring, f32x16 (&acc)[4][2], int tid, int wm, int wn,
;                   int r, int h, int st0, bool pre, const bf16_t* AgN, const bf16_t* BgN) {
;     ...
;   for (int kt = 0; kt < nk - 1; ++kt) {
;     asm volatile("s_waitcnt vmcnt(6)" ::: "memory");
;     __builtin_amdgcn_s_barrier();
;     if (kt + 2 < nk) dma_issue(Ag, lda, Bg, ldb, kt + 2, ring + (st == 0 ? 2 : st - 1) * STG, wid, lane);
;     const unsigned so = (unsigned)st * (unsigned)(STG * 2);
;     g_compute_asm<VT>(oA0 + so, oA1 + so, oB0 + so, oB1 + so, acc);
;     st = st == 2 ? 0 : st + 1;
;   }
;   asm volatile("s_waitcnt vmcnt(0)" ::: "memory");
;   __builtin_amdgcn_s_barrier();
.LBB0_1315:
	s_mul_i32 s22, s19, 0x3000
	s_addk_i32 s22, 0xd000
	s_cmp_lg_u32 s19, 0
	s_cselect_b32 s22, s22, 0x6000
	s_lshl_b32 s22, s22, 1
	v_lshl_add_u32 v32, v152, 1, s22
	v_lshl_add_u32 v158, v153, 1, s22
	v_readfirstlane_b32 s23, v32
	v_lshl_add_u64 v[156:157], v[140:141], 0, s[8:9]
	s_mov_b32 m0, s23
	v_readfirstlane_b32 s23, v158
	v_add_u32_e32 v159, s22, v154
	s_waitcnt vmcnt(6)
	s_barrier
	global_load_lds_dwordx4 v[156:157], off
	v_lshl_add_u64 v[156:157], v[138:139], 0, s[8:9]
	s_mov_b32 m0, s23
	v_readfirstlane_b32 s23, v159
	v_add_u32_e32 v159, s22, v155
	global_load_lds_dwordx4 v[156:157], off
	v_lshl_add_u64 v[156:157], v[136:137], 0, s[8:9]
	s_mov_b32 m0, s23
	v_readfirstlane_b32 s22, v159
	v_add_u32_e32 v32, 0x4000, v32
	global_load_lds_dwordx4 v[156:157], off
	v_lshl_add_u64 v[156:157], v[134:135], 0, s[8:9]
	s_mov_b32 m0, s22
	v_readfirstlane_b32 s22, v32
	v_add_u32_e32 v32, 0x4000, v158
	global_load_lds_dwordx4 v[156:157], off
	v_lshl_add_u64 v[156:157], v[132:133], 0, s[8:9]
	s_mov_b32 m0, s22
	v_readfirstlane_b32 s22, v32
	global_load_lds_dwordx4 v[156:157], off
	v_lshl_add_u64 v[156:157], v[130:131], 0, s[8:9]
	s_mov_b32 m0, s22
	s_mul_i32 s22, s19, 0x6000
	global_load_lds_dwordx4 v[156:157], off
	v_add_u32_e32 v164, s22, v149
	v_add_u32_e32 v32, s22, v147
	v_add_u32_e32 v188, s22, v150
	ds_read_b128 v[156:159], v164 offset:0
	ds_read_b128 v[160:163], v164 offset:2048
	ds_read_b128 v[164:167], v32 offset:0
	ds_read_b128 v[168:171], v32 offset:2048
	ds_read_b128 v[172:175], v32 offset:4096
	ds_read_b128 v[176:179], v32 offset:6144
	v_add_u32_e32 v204, s22, v148
	ds_read_b128 v[180:183], v188 offset:0
	ds_read_b128 v[184:187], v188 offset:2048
	ds_read_b128 v[188:191], v204 offset:0
	ds_read_b128 v[192:195], v204 offset:2048
	ds_read_b128 v[196:199], v204 offset:4096
	ds_read_b128 v[200:203], v204 offset:6144
	s_waitcnt lgkmcnt(6)
	s_nop 0
	v_mfma_f32_32x32x16_bf16 v[114:129], v[156:159], v[164:167], v[114:129]
	v_mfma_f32_32x32x16_bf16 v[98:113], v[160:163], v[164:167], v[98:113]
	v_mfma_f32_32x32x16_bf16 v[82:97], v[156:159], v[168:171], v[82:97]
	v_mfma_f32_32x32x16_bf16 v[66:81], v[160:163], v[168:171], v[66:81]
	v_mfma_f32_32x32x16_bf16 v[50:65], v[156:159], v[172:175], v[50:65]
	v_mfma_f32_32x32x16_bf16 v[34:49], v[160:163], v[172:175], v[34:49]
	v_mfma_f32_32x32x16_bf16 v[16:31], v[156:159], v[176:179], v[16:31]
	v_mfma_f32_32x32x16_bf16 v[0:15], v[160:163], v[176:179], v[0:15]
	s_waitcnt lgkmcnt(0)
	s_add_i32 s22, s19, 1
	v_mfma_f32_32x32x16_bf16 v[114:129], v[180:183], v[188:191], v[114:129]
	s_cmp_lg_u32 s19, 2
	s_cselect_b32 s19, s22, 0
	s_add_u32 s8, s8, 64
	s_addc_u32 s9, s9, 0
	s_cmpk_eq_i32 s8, 0x1580
	v_mfma_f32_32x32x16_bf16 v[98:113], v[184:187], v[188:191], v[98:113]
	v_mfma_f32_32x32x16_bf16 v[82:97], v[180:183], v[192:195], v[82:97]
	v_mfma_f32_32x32x16_bf16 v[66:81], v[184:187], v[192:195], v[66:81]
	v_mfma_f32_32x32x16_bf16 v[50:65], v[180:183], v[196:199], v[50:65]
	v_mfma_f32_32x32x16_bf16 v[34:49], v[184:187], v[196:199], v[34:49]
	v_mfma_f32_32x32x16_bf16 v[16:31], v[180:183], v[200:203], v[16:31]
	v_mfma_f32_32x32x16_bf16 v[0:15], v[184:187], v[200:203], v[0:15]
	s_cbranch_scc0 .LBB0_1315
	s_mul_i32 s8, s19, 0x6000
	s_waitcnt vmcnt(6)
	s_barrier
	v_add_u32_e32 v32, s8, v147
	v_add_u32_e32 v140, s8, v149
	ds_read_b128 v[132:135], v140 offset:0
	ds_read_b128 v[136:139], v140 offset:2048
	ds_read_b128 v[152:155], v32 offset:0
	ds_read_b128 v[156:159], v32 offset:2048
	ds_read_b128 v[160:163], v32 offset:4096
	ds_read_b128 v[164:167], v32 offset:6144
	v_add_u32_e32 v131, s8, v148
	v_add_u32_e32 v141, s8, v150
	ds_read_b128 v[168:171], v141 offset:0
	ds_read_b128 v[172:175], v141 offset:2048
	ds_read_b128 v[176:179], v131 offset:0
	ds_read_b128 v[180:183], v131 offset:2048
	ds_read_b128 v[184:187], v131 offset:4096
	ds_read_b128 v[188:191], v131 offset:6144
	s_waitcnt lgkmcnt(6)
	v_lshl_or_b32 v130, v151, 6, s21
	v_mfma_f32_32x32x16_bf16 v[98:113], v[136:139], v[152:155], v[98:113]
	v_mfma_f32_32x32x16_bf16 v[82:97], v[132:135], v[156:159], v[82:97]
	v_mfma_f32_32x32x16_bf16 v[66:81], v[136:139], v[156:159], v[66:81]
	v_mfma_f32_32x32x16_bf16 v[50:65], v[132:135], v[160:163], v[50:65]
	v_mfma_f32_32x32x16_bf16 v[34:49], v[136:139], v[160:163], v[34:49]
	v_mfma_f32_32x32x16_bf16 v[16:31], v[132:135], v[164:167], v[16:31]
	v_mfma_f32_32x32x16_bf16 v[0:15], v[136:139], v[164:167], v[0:15]
	v_mfma_f32_32x32x16_bf16 v[114:129], v[132:135], v[152:155], v[114:129]
	s_waitcnt lgkmcnt(0)
	s_add_i32 s8, s19, 1
	v_mfma_f32_32x32x16_bf16 v[98:113], v[172:175], v[176:179], v[98:113]
	s_cmp_lg_u32 s19, 2
	s_cselect_b32 s19, s8, 0
	s_mul_i32 s8, s19, 0x6000
	s_waitcnt vmcnt(0)
	s_barrier
; DI u32x2 pack4(float a, float b, float c, float d) { u32x2 w; w.x = pack2(a, b); w.y = pack2(c, d); return w; }
;     ...
;   if (Epi::STAGED) __syncthreads();
;   float* stg = Epi::CHAIN ? (float*)(smem + st_last * (STG * 2) + wid * 6144) : (float*)smem + wid * 2176;
;   if (pm == 0) epi(acc, vt, m0 + wm * 128, n0 + wn * 64, r, h, sR + wm * 128, stg);
;   DI void operator()(const f32x16 (&acc)[4][2], bool vt, int row0, int col0, int r, int h, const float* sR, float* stage) const {
;     const int lane = h * 32 + r, lr = lane >> 4, lc = (lane & 15) * 4;
; #pragma unroll
;     for (int mi = 0; mi < 4; ++mi) {
; #pragma unroll
;       for (int ni = 0; ni < 2; ++ni)
; #pragma unroll
;         for (int g = 0; g < 4; ++g)
;           *(f32x4*)(stage + r * 68 + ni * 32 + 8 * g + 4 * h) = (f32x4){acc[mi][ni][4 * g], acc[mi][ni][4 * g + 1], acc[mi][ni][4 * g + 2], acc[mi][ni][4 * g + 3]};
; #pragma unroll
;       for (int j = 0; j < 8; ++j) {
;         const int rr = j * 4 + lr;
;         f32x4 v = *(const f32x4*)(stage + rr * 68 + lc);
;         const size_t row = row0 + mi * 32 + rr, idx = row * DM + col0 + lc;
;         const f32x4 xin = *(const f32x4*)(rin + idx);
;         v += xin;
;         *(f32x4*)(out + idx) = v;
;         *(u32x2*)(xb + row * LDX + col0 + lc) = pack4(v.x, v.y, v.z, v.w);
	v_add_u32_e32 v32, s8, v147
	v_add_u32_e32 v131, s8, v148
	v_mfma_f32_32x32x16_bf16 v[82:97], v[168:171], v[180:183], v[82:97]
	v_add_u32_e32 v140, s8, v149
	v_add_u32_e32 v141, s8, v150
	ds_read_b128 v[132:135], v140 offset:0
	ds_read_b128 v[136:139], v140 offset:2048
	ds_read_b128 v[148:151], v32 offset:0
	ds_read_b128 v[152:155], v32 offset:2048
	ds_read_b128 v[156:159], v32 offset:4096
	v_mfma_f32_32x32x16_bf16 v[66:81], v[172:175], v[180:183], v[66:81]
	ds_read_b128 v[160:163], v32 offset:6144
	ds_read_b128 v[164:167], v141 offset:0
	v_mfma_f32_32x32x16_bf16 v[50:65], v[168:171], v[184:187], v[50:65]
	v_mfma_f32_32x32x16_bf16 v[34:49], v[172:175], v[184:187], v[34:49]
	v_mfma_f32_32x32x16_bf16 v[16:31], v[168:171], v[188:191], v[16:31]
	v_mfma_f32_32x32x16_bf16 v[0:15], v[172:175], v[188:191], v[0:15]
	v_mfma_f32_32x32x16_bf16 v[114:129], v[168:171], v[176:179], v[114:129]
	ds_read_b128 v[168:171], v141 offset:2048
	ds_read_b128 v[172:175], v131 offset:0
	ds_read_b128 v[176:179], v131 offset:2048
	ds_read_b128 v[180:183], v131 offset:4096
	ds_read_b128 v[184:187], v131 offset:6144
	s_waitcnt lgkmcnt(6)
	s_nop 0
	v_mfma_f32_32x32x16_bf16 v[98:113], v[136:139], v[148:151], v[98:113]
	v_mfma_f32_32x32x16_bf16 v[82:97], v[132:135], v[152:155], v[82:97]
	v_mfma_f32_32x32x16_bf16 v[66:81], v[136:139], v[152:155], v[66:81]
	v_mfma_f32_32x32x16_bf16 v[50:65], v[132:135], v[156:159], v[50:65]
	v_mfma_f32_32x32x16_bf16 v[34:49], v[136:139], v[156:159], v[34:49]
	v_mfma_f32_32x32x16_bf16 v[16:31], v[132:135], v[160:163], v[16:31]
	v_mfma_f32_32x32x16_bf16 v[0:15], v[136:139], v[160:163], v[0:15]
	v_mfma_f32_32x32x16_bf16 v[114:129], v[132:135], v[148:151], v[114:129]
	s_waitcnt lgkmcnt(0)
	v_mfma_f32_32x32x16_bf16 v[114:129], v[164:167], v[172:175], v[114:129]
	v_mfma_f32_32x32x16_bf16 v[98:113], v[168:171], v[172:175], v[98:113]
	v_mfma_f32_32x32x16_bf16 v[82:97], v[164:167], v[176:179], v[82:97]
	v_mfma_f32_32x32x16_bf16 v[66:81], v[168:171], v[176:179], v[66:81]
	v_mfma_f32_32x32x16_bf16 v[50:65], v[164:167], v[180:183], v[50:65]
	v_mfma_f32_32x32x16_bf16 v[34:49], v[168:171], v[180:183], v[34:49]
	v_mfma_f32_32x32x16_bf16 v[16:31], v[164:167], v[184:187], v[16:31]
	v_mfma_f32_32x32x16_bf16 v[0:15], v[168:171], v[184:187], v[0:15]
	s_waitcnt vmcnt(0) lgkmcnt(0)
	s_barrier
	s_movk_i32 s98, 0x110
	v_and_b32_e32 v130, 15, v242
	v_bfe_u32 v131, v242, 4, 2
	v_and_b32_e32 v132, 31, v242
	v_bfe_u32 v133, v242, 5, 1
	v_lshrrev_b32_e32 v134, 6, v242
	v_mul_u32_u24_e32 v135, 0x2200, v134
	v_mov_b32_e32 v136, v135
	v_mad_u32_u24 v135, v132, s98, v135
	v_lshl_add_u32 v135, v133, 4, v135
	v_mad_u32_u24 v136, v131, s98, v136
	v_lshl_add_u32 v136, v130, 4, v136
	v_lshrrev_b32_e32 v137, 1, v134
	v_lshlrev_b32_e32 v137, 7, v137
	v_add_u32_e32 v137, s20, v137
	v_add_u32_e32 v137, v137, v131
	v_and_b32_e32 v146, 1, v134
	v_lshlrev_b32_e32 v146, 6, v146
	v_add_u32_e32 v146, s21, v146
	v_lshl_add_u32 v154, v130, 2, v146
	v_lshlrev_b32_e32 v148, 12, v137
	v_lshl_add_u32 v148, v154, 2, v148
	v_mov_b32_e32 v149, 0
	v_lshl_add_u64 v[138:139], s[0:1], 0, v[148:149]
	v_lshl_add_u64 v[140:141], s[0:1], 0, v[148:149]
	v_mul_u32_u24_e32 v150, 0x880, v137
	v_lshl_add_u32 v150, v154, 1, v150
	v_mov_b32_e32 v151, 0
	v_lshl_add_u64 v[142:143], s[2:3], 0, v[150:151]
	v_lshrrev_b32_e32 v152, 6, v146
	v_lshlrev_b32_e32 v152, 2, v152
	v_lshl_add_u32 v152, v137, 6, v152
	v_mov_b32_e32 v153, 0
	v_lshl_add_u64 v[144:145], s[4:5], 0, v[152:153]
	v_cmp_eq_u32_e64 s[8:9], 0, v130
	s_movk_i32 s98, 0x4000
	s_mov_b32 s99, 0
	s_movk_i32 vcc_lo, 0x2200
	s_mov_b32 vcc_hi, 0
	v_mov_b32_e32 v154, v138
	v_mov_b32_e32 v155, v139
	global_load_dwordx4 v[156:159], v[154:155], off
	v_lshl_add_u64 v[154:155], v[154:155], 0, s[98:99]
	global_load_dwordx4 v[160:163], v[154:155], off
	v_lshl_add_u64 v[154:155], v[154:155], 0, s[98:99]
	global_load_dwordx4 v[164:167], v[154:155], off
	v_lshl_add_u64 v[154:155], v[154:155], 0, s[98:99]
	global_load_dwordx4 v[168:171], v[154:155], off
	v_lshl_add_u64 v[154:155], v[154:155], 0, s[98:99]
	global_load_dwordx4 v[172:175], v[154:155], off
	v_lshl_add_u64 v[154:155], v[154:155], 0, s[98:99]
	global_load_dwordx4 v[176:179], v[154:155], off
	v_lshl_add_u64 v[154:155], v[154:155], 0, s[98:99]
	global_load_dwordx4 v[180:183], v[154:155], off
	v_lshl_add_u64 v[154:155], v[154:155], 0, s[98:99]
	global_load_dwordx4 v[184:187], v[154:155], off
	v_lshl_add_u64 v[138:139], s[98:99], 3, v[138:139]
	ds_write_b128 v135, v[114:117]
	ds_write_b128 v135, v[118:121] offset:32
	ds_write_b128 v135, v[122:125] offset:64
	ds_write_b128 v135, v[126:129] offset:96
	ds_write_b128 v135, v[98:101] offset:128
	ds_write_b128 v135, v[102:105] offset:160
	ds_write_b128 v135, v[106:109] offset:192
	ds_write_b128 v135, v[110:113] offset:224
	v_mov_b32_e32 v154, v138
	v_mov_b32_e32 v155, v139
	global_load_dwordx4 v[98:101], v[154:155], off
	v_lshl_add_u64 v[154:155], v[154:155], 0, s[98:99]
	global_load_dwordx4 v[102:105], v[154:155], off
	v_lshl_add_u64 v[154:155], v[154:155], 0, s[98:99]
	global_load_dwordx4 v[106:109], v[154:155], off
	v_lshl_add_u64 v[154:155], v[154:155], 0, s[98:99]
	global_load_dwordx4 v[110:113], v[154:155], off
	v_lshl_add_u64 v[154:155], v[154:155], 0, s[98:99]
	global_load_dwordx4 v[114:117], v[154:155], off
	v_lshl_add_u64 v[154:155], v[154:155], 0, s[98:99]
	global_load_dwordx4 v[118:121], v[154:155], off
	v_lshl_add_u64 v[154:155], v[154:155], 0, s[98:99]
	global_load_dwordx4 v[122:125], v[154:155], off
	v_lshl_add_u64 v[154:155], v[154:155], 0, s[98:99]
	global_load_dwordx4 v[126:129], v[154:155], off
	v_lshl_add_u64 v[138:139], s[98:99], 3, v[138:139]
	s_waitcnt vmcnt(8)
; DI u32x2 pack4(float a, float b, float c, float d) { u32x2 w; w.x = pack2(a, b); w.y = pack2(c, d); return w; }
;   DI void operator()(const f32x16 (&acc)[4][2], bool vt, int row0, int col0, int r, int h, const float* sR, float* stage) const {
;     ...
;       for (int j = 0; j < 8; ++j) {
;         const int rr = j * 4 + lr;
;         f32x4 v = *(const f32x4*)(stage + rr * 68 + lc);
;         const size_t row = row0 + mi * 32 + rr, idx = row * DM + col0 + lc;
;         const f32x4 xin = *(const f32x4*)(rin + idx);
;         v += xin;
;         *(f32x4*)(out + idx) = v;
;         *(u32x2*)(xb + row * LDX + col0 + lc) = pack4(v.x, v.y, v.z, v.w);
;         float ss = (v.x * v.x + v.y * v.y) + (v.z * v.z + v.w * v.w);
;         ss += __shfl_xor(ss, 1); ss += __shfl_xor(ss, 2); ss += __shfl_xor(ss, 4); ss += __shfl_xor(ss, 8);
;         if ((lane & 15) == 0) ssq[row * 16 + (col0 >> 6)] = ss;
	ds_read_b128 v[188:191], v136
	ds_read_b128 v[192:195], v136 offset:1088
	ds_read_b128 v[196:199], v136 offset:2176
	ds_read_b128 v[200:203], v136 offset:3264
	s_waitcnt lgkmcnt(0)
	v_pk_add_f32 v[158:159], v[190:191], v[158:159]
	v_pk_add_f32 v[156:157], v[188:189], v[156:157]
	v_mul_f32_e32 v188, v159, v159
	v_mul_f32_e32 v146, v157, v157
	v_fmac_f32_e32 v146, v156, v156
	v_fmac_f32_e32 v188, v158, v158
	global_store_dwordx4 v[140:141], v[156:159], off
	v_add_f32_e32 v146, v146, v188
	v_cvt_pk_bf16_f32 v154, v156, v157
	v_cvt_pk_bf16_f32 v155, v158, v159
	v_lshl_add_u64 v[140:141], v[140:141], 0, s[98:99]
	global_store_dwordx2 v[142:143], v[154:155], off
	v_lshl_add_u64 v[142:143], v[142:143], 0, vcc
	v_pk_add_f32 v[162:163], v[194:195], v[162:163]
	v_pk_add_f32 v[160:161], v[192:193], v[160:161]
	v_mul_f32_e32 v192, v163, v163
	v_mul_f32_e32 v147, v161, v161
	v_fmac_f32_e32 v147, v160, v160
	v_fmac_f32_e32 v192, v162, v162
	global_store_dwordx4 v[140:141], v[160:163], off
	v_add_f32_e32 v147, v147, v192
	v_cvt_pk_bf16_f32 v204, v160, v161
	v_cvt_pk_bf16_f32 v205, v162, v163
	v_lshl_add_u64 v[140:141], v[140:141], 0, s[98:99]
	global_store_dwordx2 v[142:143], v[204:205], off
	v_lshl_add_u64 v[142:143], v[142:143], 0, vcc
	v_pk_add_f32 v[166:167], v[198:199], v[166:167]
	v_pk_add_f32 v[164:165], v[196:197], v[164:165]
	v_mul_f32_e32 v196, v167, v167
	v_mul_f32_e32 v148, v165, v165
	v_fmac_f32_e32 v148, v164, v164
	v_fmac_f32_e32 v196, v166, v166
	global_store_dwordx4 v[140:141], v[164:167], off
	v_add_f32_e32 v148, v148, v196
	v_cvt_pk_bf16_f32 v154, v164, v165
	v_cvt_pk_bf16_f32 v155, v166, v167
	v_lshl_add_u64 v[140:141], v[140:141], 0, s[98:99]
	global_store_dwordx2 v[142:143], v[154:155], off
	v_lshl_add_u64 v[142:143], v[142:143], 0, vcc
	v_pk_add_f32 v[170:171], v[202:203], v[170:171]
	v_pk_add_f32 v[168:169], v[200:201], v[168:169]
	v_mul_f32_e32 v200, v171, v171
	v_mul_f32_e32 v149, v169, v169
	v_fmac_f32_e32 v149, v168, v168
	v_fmac_f32_e32 v200, v170, v170
	global_store_dwordx4 v[140:141], v[168:171], off
	v_add_f32_e32 v149, v149, v200
	v_cvt_pk_bf16_f32 v204, v168, v169
	v_cvt_pk_bf16_f32 v205, v170, v171
	v_lshl_add_u64 v[140:141], v[140:141], 0, s[98:99]
	global_store_dwordx2 v[142:143], v[204:205], off
	v_lshl_add_u64 v[142:143], v[142:143], 0, vcc
	ds_read_b128 v[188:191], v136 offset:4352
	ds_read_b128 v[192:195], v136 offset:5440
	ds_read_b128 v[196:199], v136 offset:6528
	ds_read_b128 v[200:203], v136 offset:7616
	s_waitcnt lgkmcnt(0)
	v_pk_add_f32 v[174:175], v[190:191], v[174:175]
	v_pk_add_f32 v[172:173], v[188:189], v[172:173]
	v_mul_f32_e32 v188, v175, v175
	v_mul_f32_e32 v150, v173, v173
	v_fmac_f32_e32 v150, v172, v172
	v_fmac_f32_e32 v188, v174, v174
	global_store_dwordx4 v[140:141], v[172:175], off
	v_add_f32_e32 v150, v150, v188
	v_cvt_pk_bf16_f32 v154, v172, v173
	v_cvt_pk_bf16_f32 v155, v174, v175
	v_lshl_add_u64 v[140:141], v[140:141], 0, s[98:99]
	global_store_dwordx2 v[142:143], v[154:155], off
	v_lshl_add_u64 v[142:143], v[142:143], 0, vcc
	v_pk_add_f32 v[178:179], v[194:195], v[178:179]
	v_pk_add_f32 v[176:177], v[192:193], v[176:177]
	v_mul_f32_e32 v192, v179, v179
	v_mul_f32_e32 v151, v177, v177
	v_fmac_f32_e32 v151, v176, v176
	v_fmac_f32_e32 v192, v178, v178
	global_store_dwordx4 v[140:141], v[176:179], off
	v_add_f32_e32 v151, v151, v192
	v_cvt_pk_bf16_f32 v204, v176, v177
	v_cvt_pk_bf16_f32 v205, v178, v179
	v_lshl_add_u64 v[140:141], v[140:141], 0, s[98:99]
	global_store_dwordx2 v[142:143], v[204:205], off
	v_lshl_add_u64 v[142:143], v[142:143], 0, vcc
	v_pk_add_f32 v[182:183], v[198:199], v[182:183]
	v_pk_add_f32 v[180:181], v[196:197], v[180:181]
	v_mul_f32_e32 v196, v183, v183
	v_mul_f32_e32 v152, v181, v181
	v_fmac_f32_e32 v152, v180, v180
	v_fmac_f32_e32 v196, v182, v182
	global_store_dwordx4 v[140:141], v[180:183], off
	v_add_f32_e32 v152, v152, v196
	v_cvt_pk_bf16_f32 v154, v180, v181
	v_cvt_pk_bf16_f32 v155, v182, v183
	v_lshl_add_u64 v[140:141], v[140:141], 0, s[98:99]
	global_store_dwordx2 v[142:143], v[154:155], off
	v_lshl_add_u64 v[142:143], v[142:143], 0, vcc
	v_pk_add_f32 v[186:187], v[202:203], v[186:187]
	v_pk_add_f32 v[184:185], v[200:201], v[184:185]
	v_mul_f32_e32 v200, v187, v187
	v_mul_f32_e32 v153, v185, v185
	v_fmac_f32_e32 v153, v184, v184
	v_fmac_f32_e32 v200, v186, v186
	global_store_dwordx4 v[140:141], v[184:187], off
	v_add_f32_e32 v153, v153, v200
	v_cvt_pk_bf16_f32 v204, v184, v185
	v_cvt_pk_bf16_f32 v205, v186, v187
	v_lshl_add_u64 v[140:141], v[140:141], 0, s[98:99]
	global_store_dwordx2 v[142:143], v[204:205], off
	v_lshl_add_u64 v[142:143], v[142:143], 0, vcc
	v_add_f32_dpp v146, v146, v146 quad_perm:[1,0,3,2] row_mask:0xf bank_mask:0xf
	v_add_f32_dpp v147, v147, v147 quad_perm:[1,0,3,2] row_mask:0xf bank_mask:0xf
	v_add_f32_dpp v148, v148, v148 quad_perm:[1,0,3,2] row_mask:0xf bank_mask:0xf
	v_add_f32_dpp v149, v149, v149 quad_perm:[1,0,3,2] row_mask:0xf bank_mask:0xf
	v_add_f32_dpp v150, v150, v150 quad_perm:[1,0,3,2] row_mask:0xf bank_mask:0xf
	v_add_f32_dpp v151, v151, v151 quad_perm:[1,0,3,2] row_mask:0xf bank_mask:0xf
	v_add_f32_dpp v152, v152, v152 quad_perm:[1,0,3,2] row_mask:0xf bank_mask:0xf
	v_add_f32_dpp v153, v153, v153 quad_perm:[1,0,3,2] row_mask:0xf bank_mask:0xf
	v_add_f32_dpp v146, v146, v146 quad_perm:[2,3,0,1] row_mask:0xf bank_mask:0xf
	v_add_f32_dpp v147, v147, v147 quad_perm:[2,3,0,1] row_mask:0xf bank_mask:0xf
	v_add_f32_dpp v148, v148, v148 quad_perm:[2,3,0,1] row_mask:0xf bank_mask:0xf
	v_add_f32_dpp v149, v149, v149 quad_perm:[2,3,0,1] row_mask:0xf bank_mask:0xf
	v_add_f32_dpp v150, v150, v150 quad_perm:[2,3,0,1] row_mask:0xf bank_mask:0xf
; DI u32x2 pack4(float a, float b, float c, float d) { u32x2 w; w.x = pack2(a, b); w.y = pack2(c, d); return w; }
;   DI void operator()(const f32x16 (&acc)[4][2], bool vt, int row0, int col0, int r, int h, const float* sR, float* stage) const {
;     ...
;     for (int mi = 0; mi < 4; ++mi) {
; #pragma unroll
;       for (int ni = 0; ni < 2; ++ni)
; #pragma unroll
;         for (int g = 0; g < 4; ++g)
;           *(f32x4*)(stage + r * 68 + ni * 32 + 8 * g + 4 * h) = (f32x4){acc[mi][ni][4 * g], acc[mi][ni][4 * g + 1], acc[mi][ni][4 * g + 2], acc[mi][ni][4 * g + 3]};
; #pragma unroll
;       for (int j = 0; j < 8; ++j) {
;         const int rr = j * 4 + lr;
;         f32x4 v = *(const f32x4*)(stage + rr * 68 + lc);
;         const size_t row = row0 + mi * 32 + rr, idx = row * DM + col0 + lc;
;         const f32x4 xin = *(const f32x4*)(rin + idx);
;         v += xin;
;         *(f32x4*)(out + idx) = v;
;         *(u32x2*)(xb + row * LDX + col0 + lc) = pack4(v.x, v.y, v.z, v.w);
;         float ss = (v.x * v.x + v.y * v.y) + (v.z * v.z + v.w * v.w);
;         ss += __shfl_xor(ss, 1); ss += __shfl_xor(ss, 2); ss += __shfl_xor(ss, 4); ss += __shfl_xor(ss, 8);
;         if ((lane & 15) == 0) ssq[row * 16 + (col0 >> 6)] = ss;
	v_add_f32_dpp v151, v151, v151 quad_perm:[2,3,0,1] row_mask:0xf bank_mask:0xf
	v_add_f32_dpp v152, v152, v152 quad_perm:[2,3,0,1] row_mask:0xf bank_mask:0xf
	v_add_f32_dpp v153, v153, v153 quad_perm:[2,3,0,1] row_mask:0xf bank_mask:0xf
	v_add_f32_dpp v146, v146, v146 row_half_mirror row_mask:0xf bank_mask:0xf
	v_add_f32_dpp v147, v147, v147 row_half_mirror row_mask:0xf bank_mask:0xf
	v_add_f32_dpp v148, v148, v148 row_half_mirror row_mask:0xf bank_mask:0xf
	v_add_f32_dpp v149, v149, v149 row_half_mirror row_mask:0xf bank_mask:0xf
	v_add_f32_dpp v150, v150, v150 row_half_mirror row_mask:0xf bank_mask:0xf
	v_add_f32_dpp v151, v151, v151 row_half_mirror row_mask:0xf bank_mask:0xf
	v_add_f32_dpp v152, v152, v152 row_half_mirror row_mask:0xf bank_mask:0xf
	v_add_f32_dpp v153, v153, v153 row_half_mirror row_mask:0xf bank_mask:0xf
	v_add_f32_dpp v146, v146, v146 row_mirror row_mask:0xf bank_mask:0xf
	v_add_f32_dpp v147, v147, v147 row_mirror row_mask:0xf bank_mask:0xf
	v_add_f32_dpp v148, v148, v148 row_mirror row_mask:0xf bank_mask:0xf
	v_add_f32_dpp v149, v149, v149 row_mirror row_mask:0xf bank_mask:0xf
	v_add_f32_dpp v150, v150, v150 row_mirror row_mask:0xf bank_mask:0xf
	v_add_f32_dpp v151, v151, v151 row_mirror row_mask:0xf bank_mask:0xf
	v_add_f32_dpp v152, v152, v152 row_mirror row_mask:0xf bank_mask:0xf
	v_add_f32_dpp v153, v153, v153 row_mirror row_mask:0xf bank_mask:0xf
	s_mov_b64 exec, s[8:9]
	global_store_dword v[144:145], v146, off
	global_store_dword v[144:145], v147, off offset:256
	global_store_dword v[144:145], v148, off offset:512
	global_store_dword v[144:145], v149, off offset:768
	global_store_dword v[144:145], v150, off offset:1024
	global_store_dword v[144:145], v151, off offset:1280
	global_store_dword v[144:145], v152, off offset:1536
	global_store_dword v[144:145], v153, off offset:1792
	s_mov_b64 exec, -1
	s_movk_i32 s98, 0x800
	v_lshl_add_u64 v[144:145], v[144:145], 0, s[98:99]
	s_movk_i32 s98, 0x4000
	ds_write_b128 v135, v[82:85]
	ds_write_b128 v135, v[86:89] offset:32
	ds_write_b128 v135, v[90:93] offset:64
	ds_write_b128 v135, v[94:97] offset:96
	ds_write_b128 v135, v[66:69] offset:128
	ds_write_b128 v135, v[70:73] offset:160
	ds_write_b128 v135, v[74:77] offset:192
	ds_write_b128 v135, v[78:81] offset:224
	v_mov_b32_e32 v154, v138
	v_mov_b32_e32 v155, v139
	global_load_dwordx4 v[156:159], v[154:155], off
	v_lshl_add_u64 v[154:155], v[154:155], 0, s[98:99]
	global_load_dwordx4 v[160:163], v[154:155], off
	v_lshl_add_u64 v[154:155], v[154:155], 0, s[98:99]
	global_load_dwordx4 v[164:167], v[154:155], off
	v_lshl_add_u64 v[154:155], v[154:155], 0, s[98:99]
	global_load_dwordx4 v[168:171], v[154:155], off
	v_lshl_add_u64 v[154:155], v[154:155], 0, s[98:99]
	global_load_dwordx4 v[172:175], v[154:155], off
	v_lshl_add_u64 v[154:155], v[154:155], 0, s[98:99]
	global_load_dwordx4 v[176:179], v[154:155], off
	v_lshl_add_u64 v[154:155], v[154:155], 0, s[98:99]
	global_load_dwordx4 v[180:183], v[154:155], off
	v_lshl_add_u64 v[154:155], v[154:155], 0, s[98:99]
	global_load_dwordx4 v[184:187], v[154:155], off
	v_lshl_add_u64 v[138:139], s[98:99], 3, v[138:139]
	s_waitcnt vmcnt(32)
	ds_read_b128 v[188:191], v136
	ds_read_b128 v[192:195], v136 offset:1088
	ds_read_b128 v[196:199], v136 offset:2176
	ds_read_b128 v[200:203], v136 offset:3264
	s_waitcnt lgkmcnt(0)
	v_pk_add_f32 v[100:101], v[190:191], v[100:101]
	v_pk_add_f32 v[98:99], v[188:189], v[98:99]
	v_mul_f32_e32 v188, v101, v101
	v_mul_f32_e32 v146, v99, v99
	v_fmac_f32_e32 v146, v98, v98
	v_fmac_f32_e32 v188, v100, v100
	global_store_dwordx4 v[140:141], v[98:101], off
	v_add_f32_e32 v146, v146, v188
	v_cvt_pk_bf16_f32 v154, v98, v99
	v_cvt_pk_bf16_f32 v155, v100, v101
	v_lshl_add_u64 v[140:141], v[140:141], 0, s[98:99]
	global_store_dwordx2 v[142:143], v[154:155], off
	v_lshl_add_u64 v[142:143], v[142:143], 0, vcc
	v_pk_add_f32 v[104:105], v[194:195], v[104:105]
	v_pk_add_f32 v[102:103], v[192:193], v[102:103]
	v_mul_f32_e32 v192, v105, v105
	v_mul_f32_e32 v147, v103, v103
	v_fmac_f32_e32 v147, v102, v102
	v_fmac_f32_e32 v192, v104, v104
	global_store_dwordx4 v[140:141], v[102:105], off
	v_add_f32_e32 v147, v147, v192
	v_cvt_pk_bf16_f32 v204, v102, v103
	v_cvt_pk_bf16_f32 v205, v104, v105
	v_lshl_add_u64 v[140:141], v[140:141], 0, s[98:99]
	global_store_dwordx2 v[142:143], v[204:205], off
	v_lshl_add_u64 v[142:143], v[142:143], 0, vcc
	v_pk_add_f32 v[108:109], v[198:199], v[108:109]
	v_pk_add_f32 v[106:107], v[196:197], v[106:107]
	v_mul_f32_e32 v196, v109, v109
	v_mul_f32_e32 v148, v107, v107
	v_fmac_f32_e32 v148, v106, v106
	v_fmac_f32_e32 v196, v108, v108
	global_store_dwordx4 v[140:141], v[106:109], off
	v_add_f32_e32 v148, v148, v196
	v_cvt_pk_bf16_f32 v154, v106, v107
	v_cvt_pk_bf16_f32 v155, v108, v109
	v_lshl_add_u64 v[140:141], v[140:141], 0, s[98:99]
	global_store_dwordx2 v[142:143], v[154:155], off
	v_lshl_add_u64 v[142:143], v[142:143], 0, vcc
	v_pk_add_f32 v[112:113], v[202:203], v[112:113]
	v_pk_add_f32 v[110:111], v[200:201], v[110:111]
	v_mul_f32_e32 v200, v113, v113
	v_mul_f32_e32 v149, v111, v111
	v_fmac_f32_e32 v149, v110, v110
	v_fmac_f32_e32 v200, v112, v112
	global_store_dwordx4 v[140:141], v[110:113], off
	v_add_f32_e32 v149, v149, v200
	v_cvt_pk_bf16_f32 v204, v110, v111
	v_cvt_pk_bf16_f32 v205, v112, v113
	v_lshl_add_u64 v[140:141], v[140:141], 0, s[98:99]
	global_store_dwordx2 v[142:143], v[204:205], off
	v_lshl_add_u64 v[142:143], v[142:143], 0, vcc
	ds_read_b128 v[188:191], v136 offset:4352
	ds_read_b128 v[192:195], v136 offset:5440
	ds_read_b128 v[196:199], v136 offset:6528
	ds_read_b128 v[200:203], v136 offset:7616
	s_waitcnt lgkmcnt(0)
; DI u32x2 pack4(float a, float b, float c, float d) { u32x2 w; w.x = pack2(a, b); w.y = pack2(c, d); return w; }
;   DI void operator()(const f32x16 (&acc)[4][2], bool vt, int row0, int col0, int r, int h, const float* sR, float* stage) const {
;     ...
;     for (int mi = 0; mi < 4; ++mi) {
; #pragma unroll
;       for (int ni = 0; ni < 2; ++ni)
; #pragma unroll
;         for (int g = 0; g < 4; ++g)
;           *(f32x4*)(stage + r * 68 + ni * 32 + 8 * g + 4 * h) = (f32x4){acc[mi][ni][4 * g], acc[mi][ni][4 * g + 1], acc[mi][ni][4 * g + 2], acc[mi][ni][4 * g + 3]};
; #pragma unroll
;       for (int j = 0; j < 8; ++j) {
;         const int rr = j * 4 + lr;
;         f32x4 v = *(const f32x4*)(stage + rr * 68 + lc);
;         const size_t row = row0 + mi * 32 + rr, idx = row * DM + col0 + lc;
;         const f32x4 xin = *(const f32x4*)(rin + idx);
;         v += xin;
;         *(f32x4*)(out + idx) = v;
;         *(u32x2*)(xb + row * LDX + col0 + lc) = pack4(v.x, v.y, v.z, v.w);
;         float ss = (v.x * v.x + v.y * v.y) + (v.z * v.z + v.w * v.w);
;         ss += __shfl_xor(ss, 1); ss += __shfl_xor(ss, 2); ss += __shfl_xor(ss, 4); ss += __shfl_xor(ss, 8);
;         if ((lane & 15) == 0) ssq[row * 16 + (col0 >> 6)] = ss;
	v_pk_add_f32 v[116:117], v[190:191], v[116:117]
	v_pk_add_f32 v[114:115], v[188:189], v[114:115]
	v_mul_f32_e32 v188, v117, v117
	v_mul_f32_e32 v150, v115, v115
	v_fmac_f32_e32 v150, v114, v114
	v_fmac_f32_e32 v188, v116, v116
	global_store_dwordx4 v[140:141], v[114:117], off
	v_add_f32_e32 v150, v150, v188
	v_cvt_pk_bf16_f32 v154, v114, v115
	v_cvt_pk_bf16_f32 v155, v116, v117
	v_lshl_add_u64 v[140:141], v[140:141], 0, s[98:99]
	global_store_dwordx2 v[142:143], v[154:155], off
	v_lshl_add_u64 v[142:143], v[142:143], 0, vcc
	v_pk_add_f32 v[120:121], v[194:195], v[120:121]
	v_pk_add_f32 v[118:119], v[192:193], v[118:119]
	v_mul_f32_e32 v192, v121, v121
	v_mul_f32_e32 v151, v119, v119
	v_fmac_f32_e32 v151, v118, v118
	v_fmac_f32_e32 v192, v120, v120
	global_store_dwordx4 v[140:141], v[118:121], off
	v_add_f32_e32 v151, v151, v192
	v_cvt_pk_bf16_f32 v204, v118, v119
	v_cvt_pk_bf16_f32 v205, v120, v121
	v_lshl_add_u64 v[140:141], v[140:141], 0, s[98:99]
	global_store_dwordx2 v[142:143], v[204:205], off
	v_lshl_add_u64 v[142:143], v[142:143], 0, vcc
	v_pk_add_f32 v[124:125], v[198:199], v[124:125]
	v_pk_add_f32 v[122:123], v[196:197], v[122:123]
	v_mul_f32_e32 v196, v125, v125
	v_mul_f32_e32 v152, v123, v123
	v_fmac_f32_e32 v152, v122, v122
	v_fmac_f32_e32 v196, v124, v124
	global_store_dwordx4 v[140:141], v[122:125], off
	v_add_f32_e32 v152, v152, v196
	v_cvt_pk_bf16_f32 v154, v122, v123
	v_cvt_pk_bf16_f32 v155, v124, v125
	v_lshl_add_u64 v[140:141], v[140:141], 0, s[98:99]
	global_store_dwordx2 v[142:143], v[154:155], off
	v_lshl_add_u64 v[142:143], v[142:143], 0, vcc
	v_pk_add_f32 v[128:129], v[202:203], v[128:129]
	v_pk_add_f32 v[126:127], v[200:201], v[126:127]
	v_mul_f32_e32 v200, v129, v129
	v_mul_f32_e32 v153, v127, v127
	v_fmac_f32_e32 v153, v126, v126
	v_fmac_f32_e32 v200, v128, v128
	global_store_dwordx4 v[140:141], v[126:129], off
	v_add_f32_e32 v153, v153, v200
	v_cvt_pk_bf16_f32 v204, v126, v127
	v_cvt_pk_bf16_f32 v205, v128, v129
	v_lshl_add_u64 v[140:141], v[140:141], 0, s[98:99]
	global_store_dwordx2 v[142:143], v[204:205], off
	v_lshl_add_u64 v[142:143], v[142:143], 0, vcc
	v_add_f32_dpp v146, v146, v146 quad_perm:[1,0,3,2] row_mask:0xf bank_mask:0xf
	v_add_f32_dpp v147, v147, v147 quad_perm:[1,0,3,2] row_mask:0xf bank_mask:0xf
	v_add_f32_dpp v148, v148, v148 quad_perm:[1,0,3,2] row_mask:0xf bank_mask:0xf
	v_add_f32_dpp v149, v149, v149 quad_perm:[1,0,3,2] row_mask:0xf bank_mask:0xf
	v_add_f32_dpp v150, v150, v150 quad_perm:[1,0,3,2] row_mask:0xf bank_mask:0xf
	v_add_f32_dpp v151, v151, v151 quad_perm:[1,0,3,2] row_mask:0xf bank_mask:0xf
	v_add_f32_dpp v152, v152, v152 quad_perm:[1,0,3,2] row_mask:0xf bank_mask:0xf
	v_add_f32_dpp v153, v153, v153 quad_perm:[1,0,3,2] row_mask:0xf bank_mask:0xf
	v_add_f32_dpp v146, v146, v146 quad_perm:[2,3,0,1] row_mask:0xf bank_mask:0xf
	v_add_f32_dpp v147, v147, v147 quad_perm:[2,3,0,1] row_mask:0xf bank_mask:0xf
	v_add_f32_dpp v148, v148, v148 quad_perm:[2,3,0,1] row_mask:0xf bank_mask:0xf
	v_add_f32_dpp v149, v149, v149 quad_perm:[2,3,0,1] row_mask:0xf bank_mask:0xf
	v_add_f32_dpp v150, v150, v150 quad_perm:[2,3,0,1] row_mask:0xf bank_mask:0xf
	v_add_f32_dpp v151, v151, v151 quad_perm:[2,3,0,1] row_mask:0xf bank_mask:0xf
	v_add_f32_dpp v152, v152, v152 quad_perm:[2,3,0,1] row_mask:0xf bank_mask:0xf
	v_add_f32_dpp v153, v153, v153 quad_perm:[2,3,0,1] row_mask:0xf bank_mask:0xf
	v_add_f32_dpp v146, v146, v146 row_half_mirror row_mask:0xf bank_mask:0xf
	v_add_f32_dpp v147, v147, v147 row_half_mirror row_mask:0xf bank_mask:0xf
	v_add_f32_dpp v148, v148, v148 row_half_mirror row_mask:0xf bank_mask:0xf
	v_add_f32_dpp v149, v149, v149 row_half_mirror row_mask:0xf bank_mask:0xf
	v_add_f32_dpp v150, v150, v150 row_half_mirror row_mask:0xf bank_mask:0xf
	v_add_f32_dpp v151, v151, v151 row_half_mirror row_mask:0xf bank_mask:0xf
	v_add_f32_dpp v152, v152, v152 row_half_mirror row_mask:0xf bank_mask:0xf
	v_add_f32_dpp v153, v153, v153 row_half_mirror row_mask:0xf bank_mask:0xf
	v_add_f32_dpp v146, v146, v146 row_mirror row_mask:0xf bank_mask:0xf
	v_add_f32_dpp v147, v147, v147 row_mirror row_mask:0xf bank_mask:0xf
	v_add_f32_dpp v148, v148, v148 row_mirror row_mask:0xf bank_mask:0xf
	v_add_f32_dpp v149, v149, v149 row_mirror row_mask:0xf bank_mask:0xf
	v_add_f32_dpp v150, v150, v150 row_mirror row_mask:0xf bank_mask:0xf
	v_add_f32_dpp v151, v151, v151 row_mirror row_mask:0xf bank_mask:0xf
	v_add_f32_dpp v152, v152, v152 row_mirror row_mask:0xf bank_mask:0xf
	v_add_f32_dpp v153, v153, v153 row_mirror row_mask:0xf bank_mask:0xf
	s_mov_b64 exec, s[8:9]
	global_store_dword v[144:145], v146, off
	global_store_dword v[144:145], v147, off offset:256
	global_store_dword v[144:145], v148, off offset:512
	global_store_dword v[144:145], v149, off offset:768
	global_store_dword v[144:145], v150, off offset:1024
	global_store_dword v[144:145], v151, off offset:1280
	global_store_dword v[144:145], v152, off offset:1536
	global_store_dword v[144:145], v153, off offset:1792
	s_mov_b64 exec, -1
	s_movk_i32 s98, 0x800
	v_lshl_add_u64 v[144:145], v[144:145], 0, s[98:99]
	s_movk_i32 s98, 0x4000
	ds_write_b128 v135, v[50:53]
	ds_write_b128 v135, v[54:57] offset:32
	ds_write_b128 v135, v[58:61] offset:64
	ds_write_b128 v135, v[62:65] offset:96
	ds_write_b128 v135, v[34:37] offset:128
	ds_write_b128 v135, v[38:41] offset:160
	ds_write_b128 v135, v[42:45] offset:192
	ds_write_b128 v135, v[46:49] offset:224
	v_mov_b32_e32 v154, v138
	v_mov_b32_e32 v155, v139
	global_load_dwordx4 v[98:101], v[154:155], off
	v_lshl_add_u64 v[154:155], v[154:155], 0, s[98:99]
	global_load_dwordx4 v[102:105], v[154:155], off
	v_lshl_add_u64 v[154:155], v[154:155], 0, s[98:99]
	global_load_dwordx4 v[106:109], v[154:155], off
	v_lshl_add_u64 v[154:155], v[154:155], 0, s[98:99]
	global_load_dwordx4 v[110:113], v[154:155], off
	v_lshl_add_u64 v[154:155], v[154:155], 0, s[98:99]
	global_load_dwordx4 v[114:117], v[154:155], off
	v_lshl_add_u64 v[154:155], v[154:155], 0, s[98:99]
	global_load_dwordx4 v[118:121], v[154:155], off
	v_lshl_add_u64 v[154:155], v[154:155], 0, s[98:99]
	global_load_dwordx4 v[122:125], v[154:155], off
	v_lshl_add_u64 v[154:155], v[154:155], 0, s[98:99]
	global_load_dwordx4 v[126:129], v[154:155], off
	v_lshl_add_u64 v[138:139], s[98:99], 3, v[138:139]
	s_waitcnt vmcnt(32)
; DI u32x2 pack4(float a, float b, float c, float d) { u32x2 w; w.x = pack2(a, b); w.y = pack2(c, d); return w; }
;   DI void operator()(const f32x16 (&acc)[4][2], bool vt, int row0, int col0, int r, int h, const float* sR, float* stage) const {
;     ...
;       for (int j = 0; j < 8; ++j) {
;         const int rr = j * 4 + lr;
;         f32x4 v = *(const f32x4*)(stage + rr * 68 + lc);
;         const size_t row = row0 + mi * 32 + rr, idx = row * DM + col0 + lc;
;         const f32x4 xin = *(const f32x4*)(rin + idx);
;         v += xin;
;         *(f32x4*)(out + idx) = v;
;         *(u32x2*)(xb + row * LDX + col0 + lc) = pack4(v.x, v.y, v.z, v.w);
;         float ss = (v.x * v.x + v.y * v.y) + (v.z * v.z + v.w * v.w);
;         ss += __shfl_xor(ss, 1); ss += __shfl_xor(ss, 2); ss += __shfl_xor(ss, 4); ss += __shfl_xor(ss, 8);
	ds_read_b128 v[188:191], v136
	ds_read_b128 v[192:195], v136 offset:1088
	ds_read_b128 v[196:199], v136 offset:2176
	ds_read_b128 v[200:203], v136 offset:3264
	s_waitcnt lgkmcnt(0)
	v_pk_add_f32 v[158:159], v[190:191], v[158:159]
	v_pk_add_f32 v[156:157], v[188:189], v[156:157]
	v_mul_f32_e32 v188, v159, v159
	v_mul_f32_e32 v146, v157, v157
	v_fmac_f32_e32 v146, v156, v156
	v_fmac_f32_e32 v188, v158, v158
	global_store_dwordx4 v[140:141], v[156:159], off
	v_add_f32_e32 v146, v146, v188
	v_cvt_pk_bf16_f32 v154, v156, v157
	v_cvt_pk_bf16_f32 v155, v158, v159
	v_lshl_add_u64 v[140:141], v[140:141], 0, s[98:99]
	global_store_dwordx2 v[142:143], v[154:155], off
	v_lshl_add_u64 v[142:143], v[142:143], 0, vcc
	v_pk_add_f32 v[162:163], v[194:195], v[162:163]
	v_pk_add_f32 v[160:161], v[192:193], v[160:161]
	v_mul_f32_e32 v192, v163, v163
	v_mul_f32_e32 v147, v161, v161
	v_fmac_f32_e32 v147, v160, v160
	v_fmac_f32_e32 v192, v162, v162
	global_store_dwordx4 v[140:141], v[160:163], off
	v_add_f32_e32 v147, v147, v192
	v_cvt_pk_bf16_f32 v204, v160, v161
	v_cvt_pk_bf16_f32 v205, v162, v163
	v_lshl_add_u64 v[140:141], v[140:141], 0, s[98:99]
	global_store_dwordx2 v[142:143], v[204:205], off
	v_lshl_add_u64 v[142:143], v[142:143], 0, vcc
	v_pk_add_f32 v[166:167], v[198:199], v[166:167]
	v_pk_add_f32 v[164:165], v[196:197], v[164:165]
	v_mul_f32_e32 v196, v167, v167
	v_mul_f32_e32 v148, v165, v165
	v_fmac_f32_e32 v148, v164, v164
	v_fmac_f32_e32 v196, v166, v166
	global_store_dwordx4 v[140:141], v[164:167], off
	v_add_f32_e32 v148, v148, v196
	v_cvt_pk_bf16_f32 v154, v164, v165
	v_cvt_pk_bf16_f32 v155, v166, v167
	v_lshl_add_u64 v[140:141], v[140:141], 0, s[98:99]
	global_store_dwordx2 v[142:143], v[154:155], off
	v_lshl_add_u64 v[142:143], v[142:143], 0, vcc
	v_pk_add_f32 v[170:171], v[202:203], v[170:171]
	v_pk_add_f32 v[168:169], v[200:201], v[168:169]
	v_mul_f32_e32 v200, v171, v171
	v_mul_f32_e32 v149, v169, v169
	v_fmac_f32_e32 v149, v168, v168
	v_fmac_f32_e32 v200, v170, v170
	global_store_dwordx4 v[140:141], v[168:171], off
	v_add_f32_e32 v149, v149, v200
	v_cvt_pk_bf16_f32 v204, v168, v169
	v_cvt_pk_bf16_f32 v205, v170, v171
	v_lshl_add_u64 v[140:141], v[140:141], 0, s[98:99]
	global_store_dwordx2 v[142:143], v[204:205], off
	v_lshl_add_u64 v[142:143], v[142:143], 0, vcc
	ds_read_b128 v[188:191], v136 offset:4352
	ds_read_b128 v[192:195], v136 offset:5440
	ds_read_b128 v[196:199], v136 offset:6528
	ds_read_b128 v[200:203], v136 offset:7616
	s_waitcnt lgkmcnt(0)
	v_pk_add_f32 v[174:175], v[190:191], v[174:175]
	v_pk_add_f32 v[172:173], v[188:189], v[172:173]
	v_mul_f32_e32 v188, v175, v175
	v_mul_f32_e32 v150, v173, v173
	v_fmac_f32_e32 v150, v172, v172
	v_fmac_f32_e32 v188, v174, v174
	global_store_dwordx4 v[140:141], v[172:175], off
	v_add_f32_e32 v150, v150, v188
	v_cvt_pk_bf16_f32 v154, v172, v173
	v_cvt_pk_bf16_f32 v155, v174, v175
	v_lshl_add_u64 v[140:141], v[140:141], 0, s[98:99]
	global_store_dwordx2 v[142:143], v[154:155], off
	v_lshl_add_u64 v[142:143], v[142:143], 0, vcc
	v_pk_add_f32 v[178:179], v[194:195], v[178:179]
	v_pk_add_f32 v[176:177], v[192:193], v[176:177]
	v_mul_f32_e32 v192, v179, v179
	v_mul_f32_e32 v151, v177, v177
	v_fmac_f32_e32 v151, v176, v176
	v_fmac_f32_e32 v192, v178, v178
	global_store_dwordx4 v[140:141], v[176:179], off
	v_add_f32_e32 v151, v151, v192
	v_cvt_pk_bf16_f32 v204, v176, v177
	v_cvt_pk_bf16_f32 v205, v178, v179
	v_lshl_add_u64 v[140:141], v[140:141], 0, s[98:99]
	global_store_dwordx2 v[142:143], v[204:205], off
	v_lshl_add_u64 v[142:143], v[142:143], 0, vcc
	v_pk_add_f32 v[182:183], v[198:199], v[182:183]
	v_pk_add_f32 v[180:181], v[196:197], v[180:181]
	v_mul_f32_e32 v196, v183, v183
	v_mul_f32_e32 v152, v181, v181
	v_fmac_f32_e32 v152, v180, v180
	v_fmac_f32_e32 v196, v182, v182
	global_store_dwordx4 v[140:141], v[180:183], off
	v_add_f32_e32 v152, v152, v196
	v_cvt_pk_bf16_f32 v154, v180, v181
	v_cvt_pk_bf16_f32 v155, v182, v183
	v_lshl_add_u64 v[140:141], v[140:141], 0, s[98:99]
	global_store_dwordx2 v[142:143], v[154:155], off
	v_lshl_add_u64 v[142:143], v[142:143], 0, vcc
	v_pk_add_f32 v[186:187], v[202:203], v[186:187]
	v_pk_add_f32 v[184:185], v[200:201], v[184:185]
	v_mul_f32_e32 v200, v187, v187
	v_mul_f32_e32 v153, v185, v185
	v_fmac_f32_e32 v153, v184, v184
	v_fmac_f32_e32 v200, v186, v186
	global_store_dwordx4 v[140:141], v[184:187], off
	v_add_f32_e32 v153, v153, v200
	v_cvt_pk_bf16_f32 v204, v184, v185
	v_cvt_pk_bf16_f32 v205, v186, v187
	v_lshl_add_u64 v[140:141], v[140:141], 0, s[98:99]
	global_store_dwordx2 v[142:143], v[204:205], off
	v_lshl_add_u64 v[142:143], v[142:143], 0, vcc
	v_add_f32_dpp v146, v146, v146 quad_perm:[1,0,3,2] row_mask:0xf bank_mask:0xf
	v_add_f32_dpp v147, v147, v147 quad_perm:[1,0,3,2] row_mask:0xf bank_mask:0xf
	v_add_f32_dpp v148, v148, v148 quad_perm:[1,0,3,2] row_mask:0xf bank_mask:0xf
	v_add_f32_dpp v149, v149, v149 quad_perm:[1,0,3,2] row_mask:0xf bank_mask:0xf
	v_add_f32_dpp v150, v150, v150 quad_perm:[1,0,3,2] row_mask:0xf bank_mask:0xf
	v_add_f32_dpp v151, v151, v151 quad_perm:[1,0,3,2] row_mask:0xf bank_mask:0xf
	v_add_f32_dpp v152, v152, v152 quad_perm:[1,0,3,2] row_mask:0xf bank_mask:0xf
	v_add_f32_dpp v153, v153, v153 quad_perm:[1,0,3,2] row_mask:0xf bank_mask:0xf
	v_add_f32_dpp v146, v146, v146 quad_perm:[2,3,0,1] row_mask:0xf bank_mask:0xf
	v_add_f32_dpp v147, v147, v147 quad_perm:[2,3,0,1] row_mask:0xf bank_mask:0xf
	v_add_f32_dpp v148, v148, v148 quad_perm:[2,3,0,1] row_mask:0xf bank_mask:0xf
	v_add_f32_dpp v149, v149, v149 quad_perm:[2,3,0,1] row_mask:0xf bank_mask:0xf
	v_add_f32_dpp v150, v150, v150 quad_perm:[2,3,0,1] row_mask:0xf bank_mask:0xf
; DI u32x2 pack4(float a, float b, float c, float d) { u32x2 w; w.x = pack2(a, b); w.y = pack2(c, d); return w; }
;   DI void operator()(const f32x16 (&acc)[4][2], bool vt, int row0, int col0, int r, int h, const float* sR, float* stage) const {
;     ...
;     for (int mi = 0; mi < 4; ++mi) {
; #pragma unroll
;       for (int ni = 0; ni < 2; ++ni)
; #pragma unroll
;         for (int g = 0; g < 4; ++g)
;           *(f32x4*)(stage + r * 68 + ni * 32 + 8 * g + 4 * h) = (f32x4){acc[mi][ni][4 * g], acc[mi][ni][4 * g + 1], acc[mi][ni][4 * g + 2], acc[mi][ni][4 * g + 3]};
; #pragma unroll
;       for (int j = 0; j < 8; ++j) {
;         const int rr = j * 4 + lr;
;         f32x4 v = *(const f32x4*)(stage + rr * 68 + lc);
;         const size_t row = row0 + mi * 32 + rr, idx = row * DM + col0 + lc;
;         const f32x4 xin = *(const f32x4*)(rin + idx);
;         v += xin;
;         *(f32x4*)(out + idx) = v;
;         *(u32x2*)(xb + row * LDX + col0 + lc) = pack4(v.x, v.y, v.z, v.w);
;         float ss = (v.x * v.x + v.y * v.y) + (v.z * v.z + v.w * v.w);
;         ss += __shfl_xor(ss, 1); ss += __shfl_xor(ss, 2); ss += __shfl_xor(ss, 4); ss += __shfl_xor(ss, 8);
;         if ((lane & 15) == 0) ssq[row * 16 + (col0 >> 6)] = ss;
	v_add_f32_dpp v151, v151, v151 quad_perm:[2,3,0,1] row_mask:0xf bank_mask:0xf
	v_add_f32_dpp v152, v152, v152 quad_perm:[2,3,0,1] row_mask:0xf bank_mask:0xf
	v_add_f32_dpp v153, v153, v153 quad_perm:[2,3,0,1] row_mask:0xf bank_mask:0xf
	v_add_f32_dpp v146, v146, v146 row_half_mirror row_mask:0xf bank_mask:0xf
	v_add_f32_dpp v147, v147, v147 row_half_mirror row_mask:0xf bank_mask:0xf
	v_add_f32_dpp v148, v148, v148 row_half_mirror row_mask:0xf bank_mask:0xf
	v_add_f32_dpp v149, v149, v149 row_half_mirror row_mask:0xf bank_mask:0xf
	v_add_f32_dpp v150, v150, v150 row_half_mirror row_mask:0xf bank_mask:0xf
	v_add_f32_dpp v151, v151, v151 row_half_mirror row_mask:0xf bank_mask:0xf
	v_add_f32_dpp v152, v152, v152 row_half_mirror row_mask:0xf bank_mask:0xf
	v_add_f32_dpp v153, v153, v153 row_half_mirror row_mask:0xf bank_mask:0xf
	v_add_f32_dpp v146, v146, v146 row_mirror row_mask:0xf bank_mask:0xf
	v_add_f32_dpp v147, v147, v147 row_mirror row_mask:0xf bank_mask:0xf
	v_add_f32_dpp v148, v148, v148 row_mirror row_mask:0xf bank_mask:0xf
	v_add_f32_dpp v149, v149, v149 row_mirror row_mask:0xf bank_mask:0xf
	v_add_f32_dpp v150, v150, v150 row_mirror row_mask:0xf bank_mask:0xf
	v_add_f32_dpp v151, v151, v151 row_mirror row_mask:0xf bank_mask:0xf
	v_add_f32_dpp v152, v152, v152 row_mirror row_mask:0xf bank_mask:0xf
	v_add_f32_dpp v153, v153, v153 row_mirror row_mask:0xf bank_mask:0xf
	s_mov_b64 exec, s[8:9]
	global_store_dword v[144:145], v146, off
	global_store_dword v[144:145], v147, off offset:256
	global_store_dword v[144:145], v148, off offset:512
	global_store_dword v[144:145], v149, off offset:768
	global_store_dword v[144:145], v150, off offset:1024
	global_store_dword v[144:145], v151, off offset:1280
	global_store_dword v[144:145], v152, off offset:1536
	global_store_dword v[144:145], v153, off offset:1792
	s_mov_b64 exec, -1
	s_movk_i32 s98, 0x800
	v_lshl_add_u64 v[144:145], v[144:145], 0, s[98:99]
	s_movk_i32 s98, 0x4000
	ds_write_b128 v135, v[16:19]
	ds_write_b128 v135, v[20:23] offset:32
	ds_write_b128 v135, v[24:27] offset:64
	ds_write_b128 v135, v[28:31] offset:96
	ds_write_b128 v135, v[0:3] offset:128
	ds_write_b128 v135, v[4:7] offset:160
	ds_write_b128 v135, v[8:11] offset:192
	ds_write_b128 v135, v[12:15] offset:224
	s_waitcnt vmcnt(24)
	ds_read_b128 v[188:191], v136
	ds_read_b128 v[192:195], v136 offset:1088
	ds_read_b128 v[196:199], v136 offset:2176
	ds_read_b128 v[200:203], v136 offset:3264
	s_waitcnt lgkmcnt(0)
	v_pk_add_f32 v[100:101], v[190:191], v[100:101]
	v_pk_add_f32 v[98:99], v[188:189], v[98:99]
	v_mul_f32_e32 v188, v101, v101
	v_mul_f32_e32 v146, v99, v99
	v_fmac_f32_e32 v146, v98, v98
	v_fmac_f32_e32 v188, v100, v100
	global_store_dwordx4 v[140:141], v[98:101], off
	v_add_f32_e32 v146, v146, v188
	v_cvt_pk_bf16_f32 v154, v98, v99
	v_cvt_pk_bf16_f32 v155, v100, v101
	v_lshl_add_u64 v[140:141], v[140:141], 0, s[98:99]
	global_store_dwordx2 v[142:143], v[154:155], off
	v_lshl_add_u64 v[142:143], v[142:143], 0, vcc
	v_pk_add_f32 v[104:105], v[194:195], v[104:105]
	v_pk_add_f32 v[102:103], v[192:193], v[102:103]
	v_mul_f32_e32 v192, v105, v105
	v_mul_f32_e32 v147, v103, v103
	v_fmac_f32_e32 v147, v102, v102
	v_fmac_f32_e32 v192, v104, v104
	global_store_dwordx4 v[140:141], v[102:105], off
	v_add_f32_e32 v147, v147, v192
	v_cvt_pk_bf16_f32 v204, v102, v103
	v_cvt_pk_bf16_f32 v205, v104, v105
	v_lshl_add_u64 v[140:141], v[140:141], 0, s[98:99]
	global_store_dwordx2 v[142:143], v[204:205], off
	v_lshl_add_u64 v[142:143], v[142:143], 0, vcc
	v_pk_add_f32 v[108:109], v[198:199], v[108:109]
	v_pk_add_f32 v[106:107], v[196:197], v[106:107]
	v_mul_f32_e32 v196, v109, v109
	v_mul_f32_e32 v148, v107, v107
	v_fmac_f32_e32 v148, v106, v106
	v_fmac_f32_e32 v196, v108, v108
	global_store_dwordx4 v[140:141], v[106:109], off
	v_add_f32_e32 v148, v148, v196
	v_cvt_pk_bf16_f32 v154, v106, v107
	v_cvt_pk_bf16_f32 v155, v108, v109
	v_lshl_add_u64 v[140:141], v[140:141], 0, s[98:99]
	global_store_dwordx2 v[142:143], v[154:155], off
	v_lshl_add_u64 v[142:143], v[142:143], 0, vcc
	v_pk_add_f32 v[112:113], v[202:203], v[112:113]
	v_pk_add_f32 v[110:111], v[200:201], v[110:111]
	v_mul_f32_e32 v200, v113, v113
	v_mul_f32_e32 v149, v111, v111
	v_fmac_f32_e32 v149, v110, v110
	v_fmac_f32_e32 v200, v112, v112
	global_store_dwordx4 v[140:141], v[110:113], off
	v_add_f32_e32 v149, v149, v200
	v_cvt_pk_bf16_f32 v204, v110, v111
	v_cvt_pk_bf16_f32 v205, v112, v113
	v_lshl_add_u64 v[140:141], v[140:141], 0, s[98:99]
	global_store_dwordx2 v[142:143], v[204:205], off
	v_lshl_add_u64 v[142:143], v[142:143], 0, vcc
	ds_read_b128 v[188:191], v136 offset:4352
	ds_read_b128 v[192:195], v136 offset:5440
	ds_read_b128 v[196:199], v136 offset:6528
	ds_read_b128 v[200:203], v136 offset:7616
	s_waitcnt lgkmcnt(0)
; DI u32x2 pack4(float a, float b, float c, float d) { u32x2 w; w.x = pack2(a, b); w.y = pack2(c, d); return w; }
;   DI void operator()(const f32x16 (&acc)[4][2], bool vt, int row0, int col0, int r, int h, const float* sR, float* stage) const {
;     ...
;       for (int j = 0; j < 8; ++j) {
;         const int rr = j * 4 + lr;
;         f32x4 v = *(const f32x4*)(stage + rr * 68 + lc);
;         const size_t row = row0 + mi * 32 + rr, idx = row * DM + col0 + lc;
;         const f32x4 xin = *(const f32x4*)(rin + idx);
;         v += xin;
;         *(f32x4*)(out + idx) = v;
;         *(u32x2*)(xb + row * LDX + col0 + lc) = pack4(v.x, v.y, v.z, v.w);
;         float ss = (v.x * v.x + v.y * v.y) + (v.z * v.z + v.w * v.w);
;         ss += __shfl_xor(ss, 1); ss += __shfl_xor(ss, 2); ss += __shfl_xor(ss, 4); ss += __shfl_xor(ss, 8);
;         if ((lane & 15) == 0) ssq[row * 16 + (col0 >> 6)] = ss;
;       }
;     }
	v_pk_add_f32 v[116:117], v[190:191], v[116:117]
	v_pk_add_f32 v[114:115], v[188:189], v[114:115]
	v_mul_f32_e32 v188, v117, v117
	v_mul_f32_e32 v150, v115, v115
	v_fmac_f32_e32 v150, v114, v114
	v_fmac_f32_e32 v188, v116, v116
	global_store_dwordx4 v[140:141], v[114:117], off
	v_add_f32_e32 v150, v150, v188
	v_cvt_pk_bf16_f32 v154, v114, v115
	v_cvt_pk_bf16_f32 v155, v116, v117
	v_lshl_add_u64 v[140:141], v[140:141], 0, s[98:99]
	global_store_dwordx2 v[142:143], v[154:155], off
	v_lshl_add_u64 v[142:143], v[142:143], 0, vcc
	v_pk_add_f32 v[120:121], v[194:195], v[120:121]
	v_pk_add_f32 v[118:119], v[192:193], v[118:119]
	v_mul_f32_e32 v192, v121, v121
	v_mul_f32_e32 v151, v119, v119
	v_fmac_f32_e32 v151, v118, v118
	v_fmac_f32_e32 v192, v120, v120
	global_store_dwordx4 v[140:141], v[118:121], off
	v_add_f32_e32 v151, v151, v192
	v_cvt_pk_bf16_f32 v204, v118, v119
	v_cvt_pk_bf16_f32 v205, v120, v121
	v_lshl_add_u64 v[140:141], v[140:141], 0, s[98:99]
	global_store_dwordx2 v[142:143], v[204:205], off
	v_lshl_add_u64 v[142:143], v[142:143], 0, vcc
	v_pk_add_f32 v[124:125], v[198:199], v[124:125]
	v_pk_add_f32 v[122:123], v[196:197], v[122:123]
	v_mul_f32_e32 v196, v125, v125
	v_mul_f32_e32 v152, v123, v123
	v_fmac_f32_e32 v152, v122, v122
	v_fmac_f32_e32 v196, v124, v124
	global_store_dwordx4 v[140:141], v[122:125], off
	v_add_f32_e32 v152, v152, v196
	v_cvt_pk_bf16_f32 v154, v122, v123
	v_cvt_pk_bf16_f32 v155, v124, v125
	v_lshl_add_u64 v[140:141], v[140:141], 0, s[98:99]
	global_store_dwordx2 v[142:143], v[154:155], off
	v_lshl_add_u64 v[142:143], v[142:143], 0, vcc
	v_pk_add_f32 v[128:129], v[202:203], v[128:129]
	v_pk_add_f32 v[126:127], v[200:201], v[126:127]
	v_mul_f32_e32 v200, v129, v129
	v_mul_f32_e32 v153, v127, v127
	v_fmac_f32_e32 v153, v126, v126
	v_fmac_f32_e32 v200, v128, v128
	global_store_dwordx4 v[140:141], v[126:129], off
	v_add_f32_e32 v153, v153, v200
	v_cvt_pk_bf16_f32 v204, v126, v127
	v_cvt_pk_bf16_f32 v205, v128, v129
	v_lshl_add_u64 v[140:141], v[140:141], 0, s[98:99]
	global_store_dwordx2 v[142:143], v[204:205], off
	v_lshl_add_u64 v[142:143], v[142:143], 0, vcc
	v_add_f32_dpp v146, v146, v146 quad_perm:[1,0,3,2] row_mask:0xf bank_mask:0xf
	v_add_f32_dpp v147, v147, v147 quad_perm:[1,0,3,2] row_mask:0xf bank_mask:0xf
	v_add_f32_dpp v148, v148, v148 quad_perm:[1,0,3,2] row_mask:0xf bank_mask:0xf
	v_add_f32_dpp v149, v149, v149 quad_perm:[1,0,3,2] row_mask:0xf bank_mask:0xf
	v_add_f32_dpp v150, v150, v150 quad_perm:[1,0,3,2] row_mask:0xf bank_mask:0xf
	v_add_f32_dpp v151, v151, v151 quad_perm:[1,0,3,2] row_mask:0xf bank_mask:0xf
	v_add_f32_dpp v152, v152, v152 quad_perm:[1,0,3,2] row_mask:0xf bank_mask:0xf
	v_add_f32_dpp v153, v153, v153 quad_perm:[1,0,3,2] row_mask:0xf bank_mask:0xf
	v_add_f32_dpp v146, v146, v146 quad_perm:[2,3,0,1] row_mask:0xf bank_mask:0xf
	v_add_f32_dpp v147, v147, v147 quad_perm:[2,3,0,1] row_mask:0xf bank_mask:0xf
	v_add_f32_dpp v148, v148, v148 quad_perm:[2,3,0,1] row_mask:0xf bank_mask:0xf
	v_add_f32_dpp v149, v149, v149 quad_perm:[2,3,0,1] row_mask:0xf bank_mask:0xf
	v_add_f32_dpp v150, v150, v150 quad_perm:[2,3,0,1] row_mask:0xf bank_mask:0xf
	v_add_f32_dpp v151, v151, v151 quad_perm:[2,3,0,1] row_mask:0xf bank_mask:0xf
	v_add_f32_dpp v152, v152, v152 quad_perm:[2,3,0,1] row_mask:0xf bank_mask:0xf
	v_add_f32_dpp v153, v153, v153 quad_perm:[2,3,0,1] row_mask:0xf bank_mask:0xf
	v_add_f32_dpp v146, v146, v146 row_half_mirror row_mask:0xf bank_mask:0xf
	v_add_f32_dpp v147, v147, v147 row_half_mirror row_mask:0xf bank_mask:0xf
	v_add_f32_dpp v148, v148, v148 row_half_mirror row_mask:0xf bank_mask:0xf
	v_add_f32_dpp v149, v149, v149 row_half_mirror row_mask:0xf bank_mask:0xf
	v_add_f32_dpp v150, v150, v150 row_half_mirror row_mask:0xf bank_mask:0xf
	v_add_f32_dpp v151, v151, v151 row_half_mirror row_mask:0xf bank_mask:0xf
	v_add_f32_dpp v152, v152, v152 row_half_mirror row_mask:0xf bank_mask:0xf
	v_add_f32_dpp v153, v153, v153 row_half_mirror row_mask:0xf bank_mask:0xf
	v_add_f32_dpp v146, v146, v146 row_mirror row_mask:0xf bank_mask:0xf
	v_add_f32_dpp v147, v147, v147 row_mirror row_mask:0xf bank_mask:0xf
	v_add_f32_dpp v148, v148, v148 row_mirror row_mask:0xf bank_mask:0xf
	v_add_f32_dpp v149, v149, v149 row_mirror row_mask:0xf bank_mask:0xf
	v_add_f32_dpp v150, v150, v150 row_mirror row_mask:0xf bank_mask:0xf
	v_add_f32_dpp v151, v151, v151 row_mirror row_mask:0xf bank_mask:0xf
	v_add_f32_dpp v152, v152, v152 row_mirror row_mask:0xf bank_mask:0xf
	v_add_f32_dpp v153, v153, v153 row_mirror row_mask:0xf bank_mask:0xf
	s_mov_b64 exec, s[8:9]
	global_store_dword v[144:145], v146, off
	global_store_dword v[144:145], v147, off offset:256
	global_store_dword v[144:145], v148, off offset:512
	global_store_dword v[144:145], v149, off offset:768
	global_store_dword v[144:145], v150, off offset:1024
	global_store_dword v[144:145], v151, off offset:1280
	global_store_dword v[144:145], v152, off offset:1536
	global_store_dword v[144:145], v153, off offset:1792
	s_mov_b64 exec, -1
	s_branch .LBB0_1313
